# speedup vs baseline: 1.0102x; 1.0021x over previous
; template <class Epi> ...
;     ...
;   const int wid = cx.tid >> 6, lane = cx.tid & 63, wr = wid >> 2, wc = wid & 3, fr = lane & 15, fq = lane >> 4;
;   const int wv1k = __builtin_amdgcn_readfirstlane(cx.tid >> 6) * 1024;
;   unsigned so0, so1;
;   { int r, c; stage_rc(cx.tid * 16, r, c); so0 = (unsigned)(r * K + c) * 2u; stage_rc(cx.tid * 16 + 8192, r, c); so1 = (unsigned)(r * K + c) * 2u; }
; template <class Epi>
; DEVINL void gemm_phase(const Ctx& cx, const u16* A, const u16* Bt, int M, int N, int K, const Epi& epi) {
;   const int nM = M >> 8, nN = N >> 8, nwg = nM * nN;
;   bool pre = false;
;   for (int t = cx.bid; t < nwg; t += cx.nb) {
;     int pm, pn; tile_coords(t, nM, nN, pm, pn);
;     int qm = -1, qn = 0;
;     if (t + cx.nb < nwg) tile_coords(t + cx.nb, nM, nN, qm, qn);
;     gemm_tile(cx, A, Bt, K, pm * BM, pn * BM, epi, pre, A, Bt, K, qm < 0 ? -1 : qm * BM, qn * BM);
.LBB0_58:
	s_cmp_eq_u32 s28, 1
	s_mov_b64 s[4:5], -1
	s_cbranch_scc0 .LBB0_69
	s_cmpk_gt_i32 s59, 0x20ff
	s_cbranch_scc1 .LBB0_68
	v_ashrrev_i32_e32 v2, 31, v150
	v_lshrrev_b32_e32 v2, 26, v2
	v_add_u32_e32 v4, v150, v2
	v_bfe_i32 v2, v150, 27, 1
	v_lshlrev_b32_e32 v0, 4, v150
	v_lshrrev_b32_e32 v2, 22, v2
	v_add_u32_e32 v2, v0, v2
	v_and_b32_e32 v2, 0xfffffc00, v2
	v_sub_u32_e32 v2, v0, v2
	v_lshrrev_b32_e32 v3, 4, v2
	v_bitop3_b32 v2, v3, v2, 32 bitop3:0x6c
	v_ashrrev_i32_e32 v6, 31, v2
	v_lshrrev_b32_e32 v6, 26, v6
	v_add_u32_e32 v6, v2, v6
	v_ashrrev_i32_e32 v7, 6, v6
	v_and_b32_e32 v6, 0xc0, v6
	v_ashrrev_i32_e32 v5, 6, v4
	v_sub_u32_e32 v2, v2, v6
	v_mov_b32_e32 v13, 1
	v_lshlrev_b32_e32 v8, 5, v5
	v_ashrrev_i16_sdwa v2, v13, sext(v2) dst_sel:DWORD dst_unused:UNUSED_PAD src0_sel:DWORD src1_sel:BYTE_0
	v_and_b32_e32 v8, 32, v8
	v_bfe_i32 v6, v2, 0, 16
	v_add_u32_e32 v0, 0x2000, v0
	v_add_u32_e32 v2, v8, v6
	v_ashrrev_i32_e32 v8, 31, v0
	v_lshrrev_b32_e32 v8, 22, v8
	v_add_u32_e32 v8, v0, v8
	v_ashrrev_i32_e32 v8, 10, v8
	v_mul_i32_i24_e32 v9, 0x400, v8
	v_sub_u32_e32 v0, v0, v9
	v_lshrrev_b32_e32 v9, 4, v0
	v_bitop3_b32 v0, v9, v0, 32 bitop3:0x6c
	v_ashrrev_i32_e32 v10, 31, v0
	v_lshrrev_b32_e32 v10, 26, v10
	v_add_u32_e32 v10, v0, v10
	v_ashrrev_i32_e32 v11, 6, v10
	v_and_b32_e32 v10, 0xc0, v10
	v_readlane_b32 s4, v255, 41
	v_sub_u32_e32 v0, v0, v10
	v_readlane_b32 s5, v255, 42
	v_lshlrev_b32_e32 v3, 3, v5
	v_ashrrev_i16_sdwa v0, v13, sext(v0) dst_sel:DWORD dst_unused:UNUSED_PAD src0_sel:DWORD src1_sel:BYTE_0
	s_mov_b32 s6, s4
	s_ashr_i32 s7, s4, 31
	v_writelane_b32 v255, s4, 41
	v_bfe_i32 v10, v0, 0, 16
	v_and_b32_e32 v0, 0x1ffff0, v3
	v_writelane_b32 v255, s5, 42
	s_lshl_b64 s[4:5], s[6:7], 6
	v_lshlrev_b32_e32 v9, 3, v8
	v_lshlrev_b32_e32 v12, 5, v8
	v_add_lshl_u32 v0, v7, v0, 11
	s_add_u32 s6, s88, s4
	v_and_b32_e32 v12, 32, v12
	v_lshl_add_u32 v0, v2, 1, v0
	v_and_b32_e32 v2, 0x1ffff0, v9
	s_addc_u32 s7, s89, s5
	v_ashrrev_i32_e32 v151, 6, v150
	v_add_u32_e32 v12, v12, v10
	v_add_lshl_u32 v2, v11, v2, 11
	s_and_b64 s[4:5], s[14:15], exec
	v_and_b32_e32 v14, 15, v150
	v_lshl_add_u32 v130, v12, 1, v2
	v_lshlrev_b32_e32 v2, 12, v151
	v_lshlrev_b32_e32 v3, 2, v150
	s_cselect_b32 s4, 48, 0
	v_and_b32_e32 v15, 48, v150
	v_and_b32_e32 v9, 0x3000, v2
	v_lshlrev_b32_e32 v2, 6, v14
	v_and_b32_e32 v3, 32, v3
	s_add_u32 s4, s6, s4
	v_bitop3_b32 v2, v2, v3, v15 bitop3:0x36
	v_readlane_b32 s6, v255, 21
	v_add_u32_e32 v18, 0, v2
	s_addc_u32 s5, s7, 0
	v_add_u32_e32 v12, s6, v2
	v_readlane_b32 s6, v255, 22
	s_load_dwordx4 s[8:11], s[88:89], 0x168
	s_load_dwordx2 s[18:19], s[4:5], 0xb0
	v_add_u32_e32 v14, s6, v2
	v_readlane_b32 s6, v255, 23
	v_lshlrev_b32_e32 v5, 14, v5
	v_and_b32_e32 v5, 0xffff8000, v5
	v_add_u32_e32 v16, s6, v2
	v_readlane_b32 s6, v255, 24
	v_ashrrev_i32_e32 v13, 8, v150
	v_lshl_add_u32 v5, v7, 11, v5
	v_add_u32_e32 v17, s6, v2
	v_lshlrev_b32_e32 v2, 6, v150
	s_movk_i32 s6, 0x3c0
	v_and_or_b32 v2, v2, s6, v15
	v_xad_u32 v15, v2, v3, 0
	v_lshlrev_b32_e32 v2, 14, v8
	v_and_b32_e32 v2, 0xffff8000, v2
	v_lshl_add_u32 v2, v11, 11, v2
	v_lshlrev_b32_e32 v3, 6, v8
	v_cmp_eq_u32_e64 s[4:5], 1, v13
	v_lshlrev_b32_e32 v13, 13, v13
	v_and_or_b32 v2, v3, 64, v2
	v_and_or_b32 v4, v4, 64, v5
	v_or_b32_e32 v19, 0x800, v13
	v_or_b32_e32 v20, 0x1000, v13
	v_or_b32_e32 v21, 0x1800, v13
	s_movk_i32 s6, 0x100
	v_lshl_add_u32 v2, v10, 1, v2
	v_mov_b32_e32 v3, v1
	v_lshl_add_u32 v4, v6, 1, v4
	v_mov_b32_e32 v5, v1
	v_mov_b32_e32 v131, v1
	v_cmp_gt_u32_e64 s[6:7], s6, v150
	s_waitcnt lgkmcnt(0)
	v_lshl_add_u64 v[132:133], s[8:9], 0, v[2:3]
	v_lshl_add_u64 v[134:135], s[8:9], 0, v[4:5]
	v_lshl_add_u64 v[136:137], s[18:19], 0, v[2:3]
	v_lshl_add_u64 v[138:139], s[18:19], 0, v[4:5]
	v_add_u32_e32 v154, v12, v9
	v_add_u32_e32 v155, v18, v13
	v_add_u32_e32 v156, v15, v19
	v_add_u32_e32 v157, v15, v20
	v_add_u32_e32 v158, v15, v21
	v_add_u32_e32 v159, v14, v9
	v_add_u32_e32 v160, v16, v9
	v_add_u32_e32 v161, v17, v9
	v_readfirstlane_b32 s20, v150
	s_nop 3
	s_lshr_b32 s20, s20, 6
	s_cmp_ge_u32 s20, 4
	s_cbranch_scc0 .Lprio_g1_done
	s_setprio 1
.Lprio_g1_done:
	s_mov_b32 s29, s59
	s_branch .LBB0_62

; #define STAGE(P, BASE, br, kt) do { const char* _gb = (const char*)((BASE) + ((long)(br) * K + (long)(kt) * BK)); \
;     __builtin_amdgcn_global_load_lds((const unsigned*)(_gb + (size_t)so0), (unsigned*)((char*)(P) + wv1k), 16, 0, 0); \
;     __builtin_amdgcn_global_load_lds((const unsigned*)(_gb + (size_t)so1), (unsigned*)((char*)(P) + wv1k + 8192), 16, 0, 0); } while (0)
; #define LDA(dst, b, h) _Pragma("unroll") for (int m = 0; m < 4; ++m) _Pragma("unroll") for (int k = 0; k < 2; ++k) \
;     dst[m][k] = *reinterpret_cast<const bf16x8*>((char*)SA(b, h) + lds_byte(wr * 64 + m * 16 + fr, k * 32 + fq * 8))
; #define LDB(dst, b, h) _Pragma("unroll") for (int n = 0; n < 2; ++n) _Pragma("unroll") for (int k = 0; k < 2; ++k) \
;     dst[n][k] = *reinterpret_cast<const bf16x8*>((char*)SB(b, h) + lds_byte(wc * 32 + n * 16 + fr, k * 32 + fq * 8))
; #define MMA(ai, bj, At_, Bt_) do { __builtin_amdgcn_s_setprio(1); \
;     _Pragma("unroll") for (int m = 0; m < 4; ++m) _Pragma("unroll") for (int n = 0; n < 2; ++n) _Pragma("unroll") for (int k = 0; k < 2; ++k) \
;       acc[ai][bj][m][n] = __builtin_amdgcn_mfma_f32_16x16x32_bf16(At_[m][k], Bt_[n][k], acc[ai][bj][m][n], 0, 0, 0); \
;     __builtin_amdgcn_s_setprio(0); } while (0)
; #define WAIT_V(n) asm volatile("s_waitcnt vmcnt(" #n ")" ::: "memory")
; #define WAIT_L(n) asm volatile("s_waitcnt lgkmcnt(" #n ")" ::: "memory")
; #define BAR __builtin_amdgcn_s_barrier()
; #define SCHED __builtin_amdgcn_sched_barrier(0)
; template <class Epi> ...
;     ...
;   for (int t = 0; t < nt - 2; t += 2) {
;     LDB(B0, 0, 0); SCHED; LDA(At, 0, 0); STAGE(SA(1, 1), A, brow + HALF, t + 1);
;     WAIT_L(8); BAR; WAIT_L(0); MMA(0, 0, At, B0); BAR; SCHED;
;     LDB(B1, 0, 1); STAGE(SB(0, 0), Bt, bcol, t + 2);
;     BAR; WAIT_L(0); MMA(0, 1, At, B1); BAR;
;     LDA(At, 0, 1); STAGE(SA(0, 0), A, brow, t + 2);
;     BAR; WAIT_L(0); MMA(1, 0, At, B0); BAR; SCHED;
;     STAGE(SB(0, 1), Bt, bcol + HALF, t + 2);
;     WAIT_V(6); BAR; MMA(1, 1, At, B1); BAR;
.LBB0_65:
	ds_read_b128 v[162:165], v154
	ds_read_b128 v[166:169], v154 offset:1024
	ds_read_b128 v[170:173], v154 offset:2048
	ds_read_b128 v[174:177], v154 offset:3072
	v_lshl_add_u64 v[210:211], v[146:147], 0, s[22:23]
	s_add_i32 s46, s31, 0xc000
	v_lshl_add_u64 v[212:213], v[210:211], 0, s[50:51]
	s_mov_b32 m0, s46
	ds_read_b128 v[178:181], v155
	ds_read_b128 v[182:185], v155 offset:1024
	ds_read_b128 v[186:189], v156
	ds_read_b128 v[190:193], v156 offset:1024
	ds_read_b128 v[194:197], v157
	ds_read_b128 v[198:201], v157 offset:1024
	ds_read_b128 v[202:205], v158
	ds_read_b128 v[206:209], v158 offset:1024
	global_load_lds_dwordx4 v[212:213], off
	v_lshl_add_u64 v[212:213], v[144:145], 0, s[22:23]
	s_add_i32 s25, s31, 0xe000
	v_lshl_add_u64 v[214:215], v[212:213], 0, s[50:51]
	s_mov_b32 m0, s25
	s_nop 0
	global_load_lds_dwordx4 v[214:215], off
	s_waitcnt lgkmcnt(8)
	s_barrier
	s_waitcnt lgkmcnt(0)
	s_waitcnt lgkmcnt(0)
	v_mfma_f32_16x16x32_bf16 v[126:129], v[178:181], v[162:165], v[126:129]
	v_mfma_f32_16x16x32_bf16 v[122:125], v[178:181], v[170:173], v[122:125]
	v_mfma_f32_16x16x32_bf16 v[118:121], v[186:189], v[162:165], v[118:121]
	v_mfma_f32_16x16x32_bf16 v[114:117], v[186:189], v[170:173], v[114:117]
	v_mfma_f32_16x16x32_bf16 v[110:113], v[194:197], v[162:165], v[110:113]
	v_mfma_f32_16x16x32_bf16 v[106:109], v[194:197], v[170:173], v[106:109]
	v_mfma_f32_16x16x32_bf16 v[102:105], v[202:205], v[162:165], v[102:105]
	v_mfma_f32_16x16x32_bf16 v[98:101], v[202:205], v[170:173], v[98:101]
	v_mfma_f32_16x16x32_bf16 v[126:129], v[182:185], v[166:169], v[126:129]
	v_mfma_f32_16x16x32_bf16 v[122:125], v[182:185], v[174:177], v[122:125]
	v_mfma_f32_16x16x32_bf16 v[118:121], v[190:193], v[166:169], v[118:121]
	v_mfma_f32_16x16x32_bf16 v[114:117], v[190:193], v[174:177], v[114:117]
	v_mfma_f32_16x16x32_bf16 v[110:113], v[198:201], v[166:169], v[110:113]
	v_mfma_f32_16x16x32_bf16 v[106:109], v[198:201], v[174:177], v[106:109]
	v_mfma_f32_16x16x32_bf16 v[102:105], v[206:209], v[166:169], v[102:105]
	v_mfma_f32_16x16x32_bf16 v[98:101], v[206:209], v[174:177], v[98:101]
	s_barrier
	v_lshl_add_u64 v[214:215], v[152:153], 0, s[22:23]
	s_mov_b32 m0, s34
	v_lshl_add_u64 v[216:217], v[214:215], 0, s[0:1]
	ds_read_b128 v[236:239], v159
	ds_read_b128 v[240:243], v159 offset:1024
	ds_read_b128 v[244:247], v159 offset:2048
	ds_read_b128 v[248:251], v159 offset:3072
	global_load_lds_dwordx4 v[216:217], off
	v_lshl_add_u64 v[216:217], v[148:149], 0, s[22:23]
	v_lshl_add_u64 v[218:219], v[216:217], 0, s[0:1]
	s_mov_b32 m0, s35
	s_nop 0
	global_load_lds_dwordx4 v[218:219], off
	s_barrier
	s_waitcnt lgkmcnt(0)
	s_waitcnt lgkmcnt(0)
	v_mfma_f32_16x16x32_bf16 v[94:97], v[178:181], v[236:239], v[94:97]
	v_mfma_f32_16x16x32_bf16 v[90:93], v[178:181], v[244:247], v[90:93]
	v_mfma_f32_16x16x32_bf16 v[86:89], v[186:189], v[236:239], v[86:89]
	v_mfma_f32_16x16x32_bf16 v[82:85], v[186:189], v[244:247], v[82:85]
	v_mfma_f32_16x16x32_bf16 v[78:81], v[194:197], v[236:239], v[78:81]
	v_mfma_f32_16x16x32_bf16 v[74:77], v[194:197], v[244:247], v[74:77]
	v_mfma_f32_16x16x32_bf16 v[70:73], v[202:205], v[236:239], v[70:73]
	v_mfma_f32_16x16x32_bf16 v[66:69], v[202:205], v[244:247], v[66:69]
	v_mfma_f32_16x16x32_bf16 v[94:97], v[182:185], v[240:243], v[94:97]
	v_mfma_f32_16x16x32_bf16 v[90:93], v[182:185], v[248:251], v[90:93]
	v_mfma_f32_16x16x32_bf16 v[86:89], v[190:193], v[240:243], v[86:89]
	v_mfma_f32_16x16x32_bf16 v[82:85], v[190:193], v[248:251], v[82:85]
	v_mfma_f32_16x16x32_bf16 v[78:81], v[198:201], v[240:243], v[78:81]
	v_mfma_f32_16x16x32_bf16 v[74:77], v[198:201], v[248:251], v[74:77]
	v_mfma_f32_16x16x32_bf16 v[70:73], v[206:209], v[240:243], v[70:73]
	v_mfma_f32_16x16x32_bf16 v[66:69], v[206:209], v[248:251], v[66:69]
	s_mov_b32 m0, s31
	v_lshl_add_u64 v[218:219], v[210:211], 0, s[0:1]
	s_barrier
	ds_read_b128 v[178:181], v155 offset:16384
	ds_read_b128 v[182:185], v155 offset:17408
	ds_read_b128 v[186:189], v156 offset:16384
	ds_read_b128 v[190:193], v156 offset:17408
	ds_read_b128 v[194:197], v157 offset:16384
	ds_read_b128 v[198:201], v157 offset:17408
	ds_read_b128 v[202:205], v158 offset:16384
	ds_read_b128 v[206:209], v158 offset:17408
	global_load_lds_dwordx4 v[218:219], off
	v_lshl_add_u64 v[218:219], v[212:213], 0, s[0:1]
	s_mov_b32 m0, s21
	s_nop 0
	global_load_lds_dwordx4 v[218:219], off
	s_barrier
	s_waitcnt lgkmcnt(0)
	s_waitcnt lgkmcnt(0)
	v_mfma_f32_16x16x32_bf16 v[62:65], v[178:181], v[162:165], v[62:65]
	v_mfma_f32_16x16x32_bf16 v[58:61], v[178:181], v[170:173], v[58:61]
	v_mfma_f32_16x16x32_bf16 v[54:57], v[186:189], v[162:165], v[54:57]
	v_mfma_f32_16x16x32_bf16 v[50:53], v[186:189], v[170:173], v[50:53]
	v_mfma_f32_16x16x32_bf16 v[46:49], v[194:197], v[162:165], v[46:49]
	v_mfma_f32_16x16x32_bf16 v[42:45], v[194:197], v[170:173], v[42:45]
	v_mfma_f32_16x16x32_bf16 v[38:41], v[202:205], v[162:165], v[38:41]
	v_mfma_f32_16x16x32_bf16 v[34:37], v[202:205], v[170:173], v[34:37]
	v_mfma_f32_16x16x32_bf16 v[62:65], v[182:185], v[166:169], v[62:65]
	v_mfma_f32_16x16x32_bf16 v[58:61], v[182:185], v[174:177], v[58:61]
	v_mfma_f32_16x16x32_bf16 v[54:57], v[190:193], v[166:169], v[54:57]
	v_mfma_f32_16x16x32_bf16 v[50:53], v[190:193], v[174:177], v[50:53]
	v_mfma_f32_16x16x32_bf16 v[46:49], v[198:201], v[166:169], v[46:49]
	v_mfma_f32_16x16x32_bf16 v[42:45], v[198:201], v[174:177], v[42:45]
	v_mfma_f32_16x16x32_bf16 v[38:41], v[206:209], v[166:169], v[38:41]
	v_mfma_f32_16x16x32_bf16 v[34:37], v[206:209], v[174:177], v[34:37]
	s_barrier
; #define STAGE(P, BASE, br, kt) do { const char* _gb = (const char*)((BASE) + ((long)(br) * K + (long)(kt) * BK)); \
;     __builtin_amdgcn_global_load_lds((const unsigned*)(_gb + (size_t)so0), (unsigned*)((char*)(P) + wv1k), 16, 0, 0); \
;     __builtin_amdgcn_global_load_lds((const unsigned*)(_gb + (size_t)so1), (unsigned*)((char*)(P) + wv1k + 8192), 16, 0, 0); } while (0)
; #define LDA(dst, b, h) _Pragma("unroll") for (int m = 0; m < 4; ++m) _Pragma("unroll") for (int k = 0; k < 2; ++k) \
;     dst[m][k] = *reinterpret_cast<const bf16x8*>((char*)SA(b, h) + lds_byte(wr * 64 + m * 16 + fr, k * 32 + fq * 8))
; #define LDB(dst, b, h) _Pragma("unroll") for (int n = 0; n < 2; ++n) _Pragma("unroll") for (int k = 0; k < 2; ++k) \
;     dst[n][k] = *reinterpret_cast<const bf16x8*>((char*)SB(b, h) + lds_byte(wc * 32 + n * 16 + fr, k * 32 + fq * 8))
; #define MMA(ai, bj, At_, Bt_) do { __builtin_amdgcn_s_setprio(1); \
;     _Pragma("unroll") for (int m = 0; m < 4; ++m) _Pragma("unroll") for (int n = 0; n < 2; ++n) _Pragma("unroll") for (int k = 0; k < 2; ++k) \
;       acc[ai][bj][m][n] = __builtin_amdgcn_mfma_f32_16x16x32_bf16(At_[m][k], Bt_[n][k], acc[ai][bj][m][n], 0, 0, 0); \
;     __builtin_amdgcn_s_setprio(0); } while (0)
; #define WAIT_V(n) asm volatile("s_waitcnt vmcnt(" #n ")" ::: "memory")
; #define WAIT_L(n) asm volatile("s_waitcnt lgkmcnt(" #n ")" ::: "memory")
; #define BAR __builtin_amdgcn_s_barrier()
; #define SCHED __builtin_amdgcn_sched_barrier(0)
; template <class Epi> ...
;     ...
;     WAIT_V(6); BAR; MMA(1, 1, At, B1); BAR;
;     LDB(B0, 1, 0); SCHED; LDA(At, 1, 0); STAGE(SA(0, 1), A, brow + HALF, t + 2);
;     WAIT_L(8); BAR; WAIT_L(0); MMA(0, 0, At, B0); BAR; SCHED;
;     LDB(B1, 1, 1); STAGE(SB(1, 0), Bt, bcol, t + 3);
;     BAR; WAIT_L(0); MMA(0, 1, At, B1); BAR;
;     LDA(At, 1, 1); STAGE(SA(1, 0), A, brow, t + 3);
;     BAR; WAIT_L(0); MMA(1, 0, At, B0); BAR; SCHED;
	s_mov_b32 m0, s38
	v_lshl_add_u64 v[162:163], v[214:215], 0, s[52:53]
	global_load_lds_dwordx4 v[162:163], off
	v_lshl_add_u64 v[162:163], v[216:217], 0, s[52:53]
	s_mov_b32 m0, s39
	s_nop 0
	global_load_lds_dwordx4 v[162:163], off
	s_waitcnt vmcnt(6)
	s_barrier
	v_mfma_f32_16x16x32_bf16 v[30:33], v[178:181], v[236:239], v[30:33]
	v_mfma_f32_16x16x32_bf16 v[26:29], v[178:181], v[244:247], v[26:29]
	v_mfma_f32_16x16x32_bf16 v[22:25], v[186:189], v[236:239], v[22:25]
	v_mfma_f32_16x16x32_bf16 v[18:21], v[186:189], v[244:247], v[18:21]
	v_mfma_f32_16x16x32_bf16 v[14:17], v[194:197], v[236:239], v[14:17]
	v_mfma_f32_16x16x32_bf16 v[10:13], v[194:197], v[244:247], v[10:13]
	v_mfma_f32_16x16x32_bf16 v[6:9], v[202:205], v[236:239], v[6:9]
	v_mfma_f32_16x16x32_bf16 v[2:5], v[202:205], v[244:247], v[2:5]
	v_mfma_f32_16x16x32_bf16 v[30:33], v[182:185], v[240:243], v[30:33]
	v_mfma_f32_16x16x32_bf16 v[26:29], v[182:185], v[248:251], v[26:29]
	v_mfma_f32_16x16x32_bf16 v[22:25], v[190:193], v[240:243], v[22:25]
	v_mfma_f32_16x16x32_bf16 v[18:21], v[190:193], v[248:251], v[18:21]
	v_mfma_f32_16x16x32_bf16 v[14:17], v[198:201], v[240:243], v[14:17]
	v_mfma_f32_16x16x32_bf16 v[10:13], v[198:201], v[248:251], v[10:13]
	v_mfma_f32_16x16x32_bf16 v[6:9], v[206:209], v[240:243], v[6:9]
	v_mfma_f32_16x16x32_bf16 v[2:5], v[206:209], v[248:251], v[2:5]
	s_barrier
	ds_read_b128 v[162:165], v160
	ds_read_b128 v[166:169], v160 offset:1024
	ds_read_b128 v[170:173], v160 offset:2048
	ds_read_b128 v[174:177], v160 offset:3072
	s_mov_b32 m0, s40
	v_lshl_add_u64 v[218:219], v[210:211], 0, s[52:53]
	ds_read_b128 v[178:181], v155 offset:32768
	ds_read_b128 v[182:185], v155 offset:33792
	ds_read_b128 v[186:189], v156 offset:32768
	ds_read_b128 v[190:193], v156 offset:33792
	ds_read_b128 v[194:197], v157 offset:32768
	ds_read_b128 v[198:201], v157 offset:33792
	ds_read_b128 v[202:205], v158 offset:32768
	ds_read_b128 v[206:209], v158 offset:33792
	global_load_lds_dwordx4 v[218:219], off
	v_lshl_add_u64 v[218:219], v[212:213], 0, s[52:53]
	s_mov_b32 m0, s41
	s_nop 0
	global_load_lds_dwordx4 v[218:219], off
	s_waitcnt lgkmcnt(8)
	s_barrier
	s_waitcnt lgkmcnt(0)
	s_waitcnt lgkmcnt(0)
	v_mfma_f32_16x16x32_bf16 v[126:129], v[178:181], v[162:165], v[126:129]
	v_mfma_f32_16x16x32_bf16 v[122:125], v[178:181], v[170:173], v[122:125]
	v_mfma_f32_16x16x32_bf16 v[118:121], v[186:189], v[162:165], v[118:121]
	v_mfma_f32_16x16x32_bf16 v[114:117], v[186:189], v[170:173], v[114:117]
	v_mfma_f32_16x16x32_bf16 v[110:113], v[194:197], v[162:165], v[110:113]
	v_mfma_f32_16x16x32_bf16 v[106:109], v[194:197], v[170:173], v[106:109]
	v_mfma_f32_16x16x32_bf16 v[102:105], v[202:205], v[162:165], v[102:105]
	v_mfma_f32_16x16x32_bf16 v[98:101], v[202:205], v[170:173], v[98:101]
	v_mfma_f32_16x16x32_bf16 v[126:129], v[182:185], v[166:169], v[126:129]
	v_mfma_f32_16x16x32_bf16 v[122:125], v[182:185], v[174:177], v[122:125]
	v_mfma_f32_16x16x32_bf16 v[118:121], v[190:193], v[166:169], v[118:121]
	v_mfma_f32_16x16x32_bf16 v[114:117], v[190:193], v[174:177], v[114:117]
	v_mfma_f32_16x16x32_bf16 v[110:113], v[198:201], v[166:169], v[110:113]
	v_mfma_f32_16x16x32_bf16 v[106:109], v[198:201], v[174:177], v[106:109]
	v_mfma_f32_16x16x32_bf16 v[102:105], v[206:209], v[166:169], v[102:105]
	v_mfma_f32_16x16x32_bf16 v[98:101], v[206:209], v[174:177], v[98:101]
	s_barrier
	s_mov_b32 m0, s26
	v_lshl_add_u64 v[218:219], v[214:215], 0, s[90:91]
	ds_read_b128 v[236:239], v161
	ds_read_b128 v[240:243], v161 offset:1024
	ds_read_b128 v[244:247], v161 offset:2048
	ds_read_b128 v[248:251], v161 offset:3072
	global_load_lds_dwordx4 v[218:219], off
	v_lshl_add_u64 v[218:219], v[216:217], 0, s[90:91]
	s_mov_b32 m0, s27
	s_nop 0
	global_load_lds_dwordx4 v[218:219], off
	s_barrier
	s_waitcnt lgkmcnt(0)
	s_waitcnt lgkmcnt(0)
	v_mfma_f32_16x16x32_bf16 v[94:97], v[178:181], v[236:239], v[94:97]
	v_mfma_f32_16x16x32_bf16 v[90:93], v[178:181], v[244:247], v[90:93]
	v_mfma_f32_16x16x32_bf16 v[86:89], v[186:189], v[236:239], v[86:89]
	v_mfma_f32_16x16x32_bf16 v[82:85], v[186:189], v[244:247], v[82:85]
	v_mfma_f32_16x16x32_bf16 v[78:81], v[194:197], v[236:239], v[78:81]
	v_mfma_f32_16x16x32_bf16 v[74:77], v[194:197], v[244:247], v[74:77]
	v_mfma_f32_16x16x32_bf16 v[70:73], v[202:205], v[236:239], v[70:73]
	v_mfma_f32_16x16x32_bf16 v[66:69], v[202:205], v[244:247], v[66:69]
	v_mfma_f32_16x16x32_bf16 v[94:97], v[182:185], v[240:243], v[94:97]
	v_mfma_f32_16x16x32_bf16 v[90:93], v[182:185], v[248:251], v[90:93]
	v_mfma_f32_16x16x32_bf16 v[86:89], v[190:193], v[240:243], v[86:89]
	v_mfma_f32_16x16x32_bf16 v[82:85], v[190:193], v[248:251], v[82:85]
	v_mfma_f32_16x16x32_bf16 v[78:81], v[198:201], v[240:243], v[78:81]
	v_mfma_f32_16x16x32_bf16 v[74:77], v[198:201], v[248:251], v[74:77]
	v_mfma_f32_16x16x32_bf16 v[70:73], v[206:209], v[240:243], v[70:73]
	v_mfma_f32_16x16x32_bf16 v[66:69], v[206:209], v[248:251], v[66:69]
	s_mov_b32 m0, s42
	v_lshl_add_u64 v[210:211], v[210:211], 0, s[90:91]
	s_barrier
	ds_read_b128 v[178:181], v155 offset:49152
	ds_read_b128 v[182:185], v155 offset:50176
	ds_read_b128 v[186:189], v156 offset:49152
	ds_read_b128 v[190:193], v156 offset:50176
	ds_read_b128 v[194:197], v157 offset:49152
	ds_read_b128 v[198:201], v157 offset:50176
	ds_read_b128 v[202:205], v158 offset:49152
	ds_read_b128 v[206:209], v158 offset:50176
	global_load_lds_dwordx4 v[210:211], off
	v_lshl_add_u64 v[210:211], v[212:213], 0, s[90:91]
	s_mov_b32 m0, s43
	s_nop 0
	global_load_lds_dwordx4 v[210:211], off
	s_barrier
; #define STAGE(P, BASE, br, kt) do { const char* _gb = (const char*)((BASE) + ((long)(br) * K + (long)(kt) * BK)); \
;     __builtin_amdgcn_global_load_lds((const unsigned*)(_gb + (size_t)so0), (unsigned*)((char*)(P) + wv1k), 16, 0, 0); \
;     __builtin_amdgcn_global_load_lds((const unsigned*)(_gb + (size_t)so1), (unsigned*)((char*)(P) + wv1k + 8192), 16, 0, 0); } while (0)
; #define LDA(dst, b, h) _Pragma("unroll") for (int m = 0; m < 4; ++m) _Pragma("unroll") for (int k = 0; k < 2; ++k) \
;     dst[m][k] = *reinterpret_cast<const bf16x8*>((char*)SA(b, h) + lds_byte(wr * 64 + m * 16 + fr, k * 32 + fq * 8))
; #define LDB(dst, b, h) _Pragma("unroll") for (int n = 0; n < 2; ++n) _Pragma("unroll") for (int k = 0; k < 2; ++k) \
;     dst[n][k] = *reinterpret_cast<const bf16x8*>((char*)SB(b, h) + lds_byte(wc * 32 + n * 16 + fr, k * 32 + fq * 8))
; #define MMA(ai, bj, At_, Bt_) do { __builtin_amdgcn_s_setprio(1); \
;     _Pragma("unroll") for (int m = 0; m < 4; ++m) _Pragma("unroll") for (int n = 0; n < 2; ++n) _Pragma("unroll") for (int k = 0; k < 2; ++k) \
;       acc[ai][bj][m][n] = __builtin_amdgcn_mfma_f32_16x16x32_bf16(At_[m][k], Bt_[n][k], acc[ai][bj][m][n], 0, 0, 0); \
;     __builtin_amdgcn_s_setprio(0); } while (0)
; #define WAIT_V(n) asm volatile("s_waitcnt vmcnt(" #n ")" ::: "memory")
; #define WAIT_L(n) asm volatile("s_waitcnt lgkmcnt(" #n ")" ::: "memory")
; #define BAR __builtin_amdgcn_s_barrier()
; #define SCHED __builtin_amdgcn_sched_barrier(0)
; template <class Epi> ...
;     ...
;     BAR; WAIT_L(0); MMA(1, 0, At, B0); BAR; SCHED;
;     STAGE(SB(1, 1), Bt, bcol + HALF, t + 3);
;     WAIT_V(6); BAR; MMA(1, 1, At, B1); BAR;
;   }
;   { LDB(B0, 0, 0); LDA(At, 0, 0); STAGE(SA(1, 1), A, brow + HALF, nt - 1);
;     BAR; WAIT_L(0); MMA(0, 0, At, B0); BAR;
;     LDB(B1, 0, 1); BAR; WAIT_L(0); MMA(0, 1, At, B1); BAR;
;     LDA(At, 0, 1); WAIT_V(4); BAR; WAIT_L(0); MMA(1, 0, At, B0); MMA(1, 1, At, B1); BAR; }
	s_waitcnt lgkmcnt(0)
	s_waitcnt lgkmcnt(0)
	v_mfma_f32_16x16x32_bf16 v[62:65], v[178:181], v[162:165], v[62:65]
	v_mfma_f32_16x16x32_bf16 v[58:61], v[178:181], v[170:173], v[58:61]
	v_mfma_f32_16x16x32_bf16 v[54:57], v[186:189], v[162:165], v[54:57]
	v_mfma_f32_16x16x32_bf16 v[50:53], v[186:189], v[170:173], v[50:53]
	v_mfma_f32_16x16x32_bf16 v[46:49], v[194:197], v[162:165], v[46:49]
	v_mfma_f32_16x16x32_bf16 v[42:45], v[194:197], v[170:173], v[42:45]
	v_mfma_f32_16x16x32_bf16 v[38:41], v[202:205], v[162:165], v[38:41]
	v_mfma_f32_16x16x32_bf16 v[34:37], v[202:205], v[170:173], v[34:37]
	v_mfma_f32_16x16x32_bf16 v[62:65], v[182:185], v[166:169], v[62:65]
	v_mfma_f32_16x16x32_bf16 v[58:61], v[182:185], v[174:177], v[58:61]
	v_mfma_f32_16x16x32_bf16 v[54:57], v[190:193], v[166:169], v[54:57]
	v_mfma_f32_16x16x32_bf16 v[50:53], v[190:193], v[174:177], v[50:53]
	v_mfma_f32_16x16x32_bf16 v[46:49], v[198:201], v[166:169], v[46:49]
	v_mfma_f32_16x16x32_bf16 v[42:45], v[198:201], v[174:177], v[42:45]
	v_mfma_f32_16x16x32_bf16 v[38:41], v[206:209], v[166:169], v[38:41]
	v_mfma_f32_16x16x32_bf16 v[34:37], v[206:209], v[174:177], v[34:37]
	s_barrier
	s_mov_b32 m0, s44
	v_lshl_add_u64 v[162:163], v[214:215], 0, s[54:55]
	global_load_lds_dwordx4 v[162:163], off
	v_lshl_add_u64 v[162:163], v[216:217], 0, s[54:55]
	s_mov_b32 m0, s45
	s_nop 0
	global_load_lds_dwordx4 v[162:163], off
	s_waitcnt vmcnt(6)
	s_barrier
	v_mfma_f32_16x16x32_bf16 v[30:33], v[178:181], v[236:239], v[30:33]
	v_mfma_f32_16x16x32_bf16 v[26:29], v[178:181], v[244:247], v[26:29]
	v_mfma_f32_16x16x32_bf16 v[22:25], v[186:189], v[236:239], v[22:25]
	v_mfma_f32_16x16x32_bf16 v[18:21], v[186:189], v[244:247], v[18:21]
	v_mfma_f32_16x16x32_bf16 v[14:17], v[194:197], v[236:239], v[14:17]
	v_mfma_f32_16x16x32_bf16 v[10:13], v[194:197], v[244:247], v[10:13]
	v_mfma_f32_16x16x32_bf16 v[6:9], v[202:205], v[236:239], v[6:9]
	v_mfma_f32_16x16x32_bf16 v[2:5], v[202:205], v[244:247], v[2:5]
	v_mfma_f32_16x16x32_bf16 v[30:33], v[182:185], v[240:243], v[30:33]
	v_mfma_f32_16x16x32_bf16 v[26:29], v[182:185], v[248:251], v[26:29]
	v_mfma_f32_16x16x32_bf16 v[22:25], v[190:193], v[240:243], v[22:25]
	v_mfma_f32_16x16x32_bf16 v[18:21], v[190:193], v[248:251], v[18:21]
	v_mfma_f32_16x16x32_bf16 v[14:17], v[198:201], v[240:243], v[14:17]
	v_mfma_f32_16x16x32_bf16 v[10:13], v[198:201], v[248:251], v[10:13]
	v_mfma_f32_16x16x32_bf16 v[6:9], v[206:209], v[240:243], v[6:9]
	v_mfma_f32_16x16x32_bf16 v[2:5], v[206:209], v[248:251], v[2:5]
	s_add_i32 s24, s24, 2
	s_add_u32 s22, s22, 0x100
	s_addc_u32 s23, s23, 0
	s_cmp_lt_u32 s24, 12
	s_barrier
	s_cbranch_scc1 .LBB0_65
	s_mov_b64 s[22:23], 0x780
	s_mov_b32 m0, s46
	v_lshl_add_u64 v[140:141], v[140:141], 0, s[22:23]
	ds_read_b128 v[144:147], v154
	ds_read_b128 v[162:165], v154 offset:1024
	ds_read_b128 v[166:169], v154 offset:2048
	ds_read_b128 v[170:173], v154 offset:3072
	ds_read_b128 v[174:177], v155
	ds_read_b128 v[178:181], v155 offset:1024
	ds_read_b128 v[182:185], v156
	ds_read_b128 v[186:189], v156 offset:1024
	ds_read_b128 v[190:193], v157
	ds_read_b128 v[194:197], v157 offset:1024
	ds_read_b128 v[198:201], v158
	ds_read_b128 v[202:205], v158 offset:1024
	global_load_lds_dwordx4 v[140:141], off
	v_lshl_add_u64 v[140:141], v[142:143], 0, s[22:23]
	s_mov_b32 m0, s25
	s_nop 0
	global_load_lds_dwordx4 v[140:141], off
	s_barrier
	s_waitcnt lgkmcnt(0)
	s_waitcnt lgkmcnt(0)
	v_mfma_f32_16x16x32_bf16 v[126:129], v[174:177], v[144:147], v[126:129]
	v_mfma_f32_16x16x32_bf16 v[122:125], v[174:177], v[166:169], v[122:125]
	v_mfma_f32_16x16x32_bf16 v[118:121], v[182:185], v[144:147], v[118:121]
	v_mfma_f32_16x16x32_bf16 v[106:109], v[190:193], v[166:169], v[106:109]
	v_mfma_f32_16x16x32_bf16 v[102:105], v[198:201], v[144:147], v[102:105]
	v_mfma_f32_16x16x32_bf16 v[126:129], v[178:181], v[162:165], v[126:129]
	v_mfma_f32_16x16x32_bf16 v[122:125], v[178:181], v[170:173], v[122:125]
	v_mfma_f32_16x16x32_bf16 v[118:121], v[186:189], v[162:165], v[118:121]
	v_mfma_f32_16x16x32_bf16 v[114:117], v[182:185], v[166:169], v[114:117]
	v_mfma_f32_16x16x32_bf16 v[110:113], v[190:193], v[144:147], v[110:113]
	v_mfma_f32_16x16x32_bf16 v[106:109], v[194:197], v[170:173], v[106:109]
	v_mfma_f32_16x16x32_bf16 v[102:105], v[202:205], v[162:165], v[102:105]
	v_mfma_f32_16x16x32_bf16 v[98:101], v[198:201], v[166:169], v[98:101]
	v_mfma_f32_16x16x32_bf16 v[140:143], v[186:189], v[170:173], v[114:117]
	v_mfma_f32_16x16x32_bf16 v[206:209], v[194:197], v[162:165], v[110:113]
	v_mfma_f32_16x16x32_bf16 v[236:239], v[202:205], v[170:173], v[98:101]
	s_barrier
	s_nop 2
	ds_read_b128 v[98:101], v159
	ds_read_b128 v[110:113], v159 offset:1024
	ds_read_b128 v[114:117], v159 offset:2048
	ds_read_b128 v[240:243], v159 offset:3072
	s_barrier
	s_waitcnt lgkmcnt(0)
	s_waitcnt lgkmcnt(0)
	v_mfma_f32_16x16x32_bf16 v[90:93], v[174:177], v[114:117], v[90:93]
	v_mfma_f32_16x16x32_bf16 v[86:89], v[182:185], v[98:101], v[86:89]
	v_mfma_f32_16x16x32_bf16 v[74:77], v[190:193], v[114:117], v[74:77]
	v_mfma_f32_16x16x32_bf16 v[70:73], v[198:201], v[98:101], v[70:73]
	v_mfma_f32_16x16x32_bf16 v[94:97], v[174:177], v[98:101], v[94:97]
	v_mfma_f32_16x16x32_bf16 v[90:93], v[178:181], v[240:243], v[90:93]
	v_mfma_f32_16x16x32_bf16 v[86:89], v[186:189], v[110:113], v[86:89]
	v_mfma_f32_16x16x32_bf16 v[82:85], v[182:185], v[114:117], v[82:85]
	v_mfma_f32_16x16x32_bf16 v[78:81], v[190:193], v[98:101], v[78:81]
	v_mfma_f32_16x16x32_bf16 v[74:77], v[194:197], v[240:243], v[74:77]
	v_mfma_f32_16x16x32_bf16 v[70:73], v[202:205], v[110:113], v[70:73]
	v_mfma_f32_16x16x32_bf16 v[66:69], v[198:201], v[114:117], v[66:69]
	v_mfma_f32_16x16x32_bf16 v[244:247], v[178:181], v[110:113], v[94:97]
	v_mfma_f32_16x16x32_bf16 v[174:177], v[186:189], v[240:243], v[82:85]
	v_mfma_f32_16x16x32_bf16 v[178:181], v[194:197], v[110:113], v[78:81]
	v_mfma_f32_16x16x32_bf16 v[182:185], v[202:205], v[240:243], v[66:69]
	s_barrier
; #define LDA(dst, b, h) _Pragma("unroll") for (int m = 0; m < 4; ++m) _Pragma("unroll") for (int k = 0; k < 2; ++k) \
;     dst[m][k] = *reinterpret_cast<const bf16x8*>((char*)SA(b, h) + lds_byte(wr * 64 + m * 16 + fr, k * 32 + fq * 8))
; #define LDB(dst, b, h) _Pragma("unroll") for (int n = 0; n < 2; ++n) _Pragma("unroll") for (int k = 0; k < 2; ++k) \
;     dst[n][k] = *reinterpret_cast<const bf16x8*>((char*)SB(b, h) + lds_byte(wc * 32 + n * 16 + fr, k * 32 + fq * 8))
; #define MMA(ai, bj, At_, Bt_) do { __builtin_amdgcn_s_setprio(1); \
;     _Pragma("unroll") for (int m = 0; m < 4; ++m) _Pragma("unroll") for (int n = 0; n < 2; ++n) _Pragma("unroll") for (int k = 0; k < 2; ++k) \
;       acc[ai][bj][m][n] = __builtin_amdgcn_mfma_f32_16x16x32_bf16(At_[m][k], Bt_[n][k], acc[ai][bj][m][n], 0, 0, 0); \
;     __builtin_amdgcn_s_setprio(0); } while (0)
; #define WAIT_V(n) asm volatile("s_waitcnt vmcnt(" #n ")" ::: "memory")
; #define WAIT_L(n) asm volatile("s_waitcnt lgkmcnt(" #n ")" ::: "memory")
; #define BAR __builtin_amdgcn_s_barrier()
; template <class Epi> ...
;     ...
;     LDA(At, 0, 1); WAIT_V(4); BAR; WAIT_L(0); MMA(1, 0, At, B0); MMA(1, 1, At, B1); BAR; }
;   { LDB(B0, 1, 0); LDA(At, 1, 0); WAIT_V(2); BAR; WAIT_L(0); MMA(0, 0, At, B0); BAR;
	s_nop 1
	ds_read_b128 v[66:69], v155 offset:16384
	ds_read_b128 v[78:81], v155 offset:17408
	ds_read_b128 v[82:85], v156 offset:16384
	ds_read_b128 v[94:97], v156 offset:17408
	ds_read_b128 v[186:189], v157 offset:16384
	ds_read_b128 v[190:193], v157 offset:17408
	ds_read_b128 v[194:197], v158 offset:16384
	ds_read_b128 v[198:201], v158 offset:17408
	s_waitcnt vmcnt(4)
	s_barrier
	s_waitcnt lgkmcnt(0)
	s_waitcnt lgkmcnt(0)
	v_mfma_f32_16x16x32_bf16 v[62:65], v[66:69], v[144:147], v[62:65]
	v_mfma_f32_16x16x32_bf16 v[58:61], v[66:69], v[166:169], v[58:61]
	v_mfma_f32_16x16x32_bf16 v[54:57], v[82:85], v[144:147], v[54:57]
	v_mfma_f32_16x16x32_bf16 v[42:45], v[186:189], v[166:169], v[42:45]
	v_mfma_f32_16x16x32_bf16 v[38:41], v[194:197], v[144:147], v[38:41]
	v_mfma_f32_16x16x32_bf16 v[62:65], v[78:81], v[162:165], v[62:65]
	v_mfma_f32_16x16x32_bf16 v[58:61], v[78:81], v[170:173], v[58:61]
	v_mfma_f32_16x16x32_bf16 v[54:57], v[94:97], v[162:165], v[54:57]
	v_mfma_f32_16x16x32_bf16 v[50:53], v[82:85], v[166:169], v[50:53]
	v_mfma_f32_16x16x32_bf16 v[46:49], v[186:189], v[144:147], v[46:49]
	v_mfma_f32_16x16x32_bf16 v[42:45], v[190:193], v[170:173], v[42:45]
	v_mfma_f32_16x16x32_bf16 v[38:41], v[198:201], v[162:165], v[38:41]
	v_mfma_f32_16x16x32_bf16 v[34:37], v[194:197], v[166:169], v[34:37]
	v_mfma_f32_16x16x32_bf16 v[202:205], v[94:97], v[170:173], v[50:53]
	v_mfma_f32_16x16x32_bf16 v[248:251], v[190:193], v[162:165], v[46:49]
	v_mfma_f32_16x16x32_bf16 v[144:147], v[198:201], v[170:173], v[34:37]
	v_mfma_f32_16x16x32_bf16 v[26:29], v[66:69], v[114:117], v[26:29]
	v_mfma_f32_16x16x32_bf16 v[22:25], v[82:85], v[98:101], v[22:25]
	v_mfma_f32_16x16x32_bf16 v[10:13], v[186:189], v[114:117], v[10:13]
	v_mfma_f32_16x16x32_bf16 v[6:9], v[194:197], v[98:101], v[6:9]
	v_mfma_f32_16x16x32_bf16 v[30:33], v[66:69], v[98:101], v[30:33]
	v_mfma_f32_16x16x32_bf16 v[26:29], v[78:81], v[240:243], v[26:29]
	v_mfma_f32_16x16x32_bf16 v[22:25], v[94:97], v[110:113], v[22:25]
	v_mfma_f32_16x16x32_bf16 v[18:21], v[82:85], v[114:117], v[18:21]
	v_mfma_f32_16x16x32_bf16 v[14:17], v[186:189], v[98:101], v[14:17]
	v_mfma_f32_16x16x32_bf16 v[10:13], v[190:193], v[240:243], v[10:13]
	v_mfma_f32_16x16x32_bf16 v[6:9], v[198:201], v[110:113], v[6:9]
	v_mfma_f32_16x16x32_bf16 v[2:5], v[194:197], v[114:117], v[2:5]
	v_mfma_f32_16x16x32_bf16 v[162:165], v[78:81], v[110:113], v[30:33]
	v_mfma_f32_16x16x32_bf16 v[166:169], v[94:97], v[240:243], v[18:21]
	v_mfma_f32_16x16x32_bf16 v[170:173], v[190:193], v[110:113], v[14:17]
	v_mfma_f32_16x16x32_bf16 v[186:189], v[198:201], v[240:243], v[2:5]
	s_barrier
	s_nop 1
	ds_read_b128 v[2:5], v160
	ds_read_b128 v[14:17], v160 offset:1024
	ds_read_b128 v[190:193], v160 offset:2048
	ds_read_b128 v[194:197], v160 offset:3072
	ds_read_b128 v[18:21], v155 offset:32768
	ds_read_b128 v[30:33], v155 offset:33792
	ds_read_b128 v[34:37], v156 offset:32768
	ds_read_b128 v[46:49], v156 offset:33792
	ds_read_b128 v[50:53], v157 offset:32768
	ds_read_b128 v[198:201], v157 offset:33792
	ds_read_b128 v[240:243], v158 offset:32768
	ds_read_b128 v[222:225], v158 offset:33792
	s_waitcnt vmcnt(2)
	s_barrier
	s_waitcnt lgkmcnt(0)
	s_waitcnt lgkmcnt(0)
	v_mfma_f32_16x16x32_bf16 v[66:69], v[18:21], v[2:5], v[126:129]
	v_mfma_f32_16x16x32_bf16 v[114:117], v[30:33], v[14:17], v[66:69]
	v_mfma_f32_16x16x32_bf16 v[66:69], v[18:21], v[190:193], v[122:125]
	v_mfma_f32_16x16x32_bf16 v[126:129], v[30:33], v[194:197], v[66:69]
	v_mfma_f32_16x16x32_bf16 v[66:69], v[34:37], v[2:5], v[118:121]
	v_mfma_f32_16x16x32_bf16 v[98:101], v[46:49], v[14:17], v[66:69]
	v_mfma_f32_16x16x32_bf16 v[66:69], v[34:37], v[190:193], v[140:143]
	v_mfma_f32_16x16x32_bf16 v[110:113], v[46:49], v[194:197], v[66:69]
	v_mfma_f32_16x16x32_bf16 v[66:69], v[50:53], v[2:5], v[206:209]
	v_mfma_f32_16x16x32_bf16 v[82:85], v[198:201], v[14:17], v[66:69]
	v_mfma_f32_16x16x32_bf16 v[66:69], v[50:53], v[190:193], v[106:109]
	v_mfma_f32_16x16x32_bf16 v[94:97], v[198:201], v[194:197], v[66:69]
	v_mfma_f32_16x16x32_bf16 v[66:69], v[240:243], v[2:5], v[102:105]
	v_mfma_f32_16x16x32_bf16 v[78:81], v[240:243], v[190:193], v[236:239]
	v_mfma_f32_16x16x32_bf16 v[66:69], v[222:225], v[14:17], v[66:69]
	v_mfma_f32_16x16x32_bf16 v[78:81], v[222:225], v[194:197], v[78:81]
	s_barrier
; #define LDA(dst, b, h) _Pragma("unroll") for (int m = 0; m < 4; ++m) _Pragma("unroll") for (int k = 0; k < 2; ++k) \
;     dst[m][k] = *reinterpret_cast<const bf16x8*>((char*)SA(b, h) + lds_byte(wr * 64 + m * 16 + fr, k * 32 + fq * 8))
; #define LDB(dst, b, h) _Pragma("unroll") for (int n = 0; n < 2; ++n) _Pragma("unroll") for (int k = 0; k < 2; ++k) \
;     dst[n][k] = *reinterpret_cast<const bf16x8*>((char*)SB(b, h) + lds_byte(wc * 32 + n * 16 + fr, k * 32 + fq * 8))
; #define MMA(ai, bj, At_, Bt_) do { __builtin_amdgcn_s_setprio(1); \
;     _Pragma("unroll") for (int m = 0; m < 4; ++m) _Pragma("unroll") for (int n = 0; n < 2; ++n) _Pragma("unroll") for (int k = 0; k < 2; ++k) \
;       acc[ai][bj][m][n] = __builtin_amdgcn_mfma_f32_16x16x32_bf16(At_[m][k], Bt_[n][k], acc[ai][bj][m][n], 0, 0, 0); \
;     __builtin_amdgcn_s_setprio(0); } while (0)
; #define WAIT_V(n) asm volatile("s_waitcnt vmcnt(" #n ")" ::: "memory")
; #define WAIT_L(n) asm volatile("s_waitcnt lgkmcnt(" #n ")" ::: "memory")
; #define BAR __builtin_amdgcn_s_barrier()
; template <class Epi> ...
;     ...
;   { LDB(B0, 1, 0); LDA(At, 1, 0); WAIT_V(2); BAR; WAIT_L(0); MMA(0, 0, At, B0); BAR;
;     LDB(B1, 1, 1); WAIT_V(0); BAR; WAIT_L(0); MMA(0, 1, At, B1); BAR;
;     LDA(At, 1, 1); BAR; WAIT_L(0); MMA(1, 0, At, B0); MMA(1, 1, At, B1); BAR; }
;   if (wr == 0) BAR;
	ds_read_b128 v[140:143], v161
	ds_read_b128 v[206:209], v161 offset:1024
	ds_read_b128 v[236:239], v161 offset:2048
	ds_read_b128 v[226:229], v161 offset:3072
	s_waitcnt vmcnt(0)
	s_barrier
	s_waitcnt lgkmcnt(0)
	s_waitcnt lgkmcnt(0)
	v_mfma_f32_16x16x32_bf16 v[102:105], v[18:21], v[140:143], v[244:247]
	v_mfma_f32_16x16x32_bf16 v[18:21], v[18:21], v[236:239], v[90:93]
	v_mfma_f32_16x16x32_bf16 v[122:125], v[30:33], v[226:229], v[18:21]
	v_mfma_f32_16x16x32_bf16 v[18:21], v[34:37], v[140:143], v[86:89]
	v_mfma_f32_16x16x32_bf16 v[118:121], v[30:33], v[206:209], v[102:105]
	v_mfma_f32_16x16x32_bf16 v[102:105], v[46:49], v[206:209], v[18:21]
	v_mfma_f32_16x16x32_bf16 v[18:21], v[34:37], v[236:239], v[174:177]
	v_mfma_f32_16x16x32_bf16 v[106:109], v[46:49], v[226:229], v[18:21]
	v_mfma_f32_16x16x32_bf16 v[18:21], v[50:53], v[140:143], v[178:181]
	v_mfma_f32_16x16x32_bf16 v[86:89], v[198:201], v[206:209], v[18:21]
	v_mfma_f32_16x16x32_bf16 v[18:21], v[50:53], v[236:239], v[74:77]
	v_mfma_f32_16x16x32_bf16 v[90:93], v[198:201], v[226:229], v[18:21]
	v_mfma_f32_16x16x32_bf16 v[18:21], v[240:243], v[140:143], v[70:73]
	v_mfma_f32_16x16x32_bf16 v[70:73], v[222:225], v[206:209], v[18:21]
	v_mfma_f32_16x16x32_bf16 v[18:21], v[240:243], v[236:239], v[182:185]
	v_mfma_f32_16x16x32_bf16 v[74:77], v[222:225], v[226:229], v[18:21]
	s_barrier
	ds_read_b128 v[174:177], v155 offset:49152
	ds_read_b128 v[178:181], v155 offset:50176
	ds_read_b128 v[182:185], v156 offset:49152
	ds_read_b128 v[198:201], v156 offset:50176
	ds_read_b128 v[222:225], v157 offset:49152
	ds_read_b128 v[240:243], v157 offset:50176
	ds_read_b128 v[244:247], v158 offset:49152
	ds_read_b128 v[230:233], v158 offset:50176
	s_barrier
	s_waitcnt lgkmcnt(0)
	s_waitcnt lgkmcnt(0)
	v_mfma_f32_16x16x32_bf16 v[18:21], v[174:177], v[2:5], v[62:65]
	v_mfma_f32_16x16x32_bf16 v[50:53], v[178:181], v[14:17], v[18:21]
	v_mfma_f32_16x16x32_bf16 v[18:21], v[174:177], v[190:193], v[58:61]
	v_mfma_f32_16x16x32_bf16 v[62:65], v[178:181], v[194:197], v[18:21]
	v_mfma_f32_16x16x32_bf16 v[18:21], v[182:185], v[2:5], v[54:57]
	v_mfma_f32_16x16x32_bf16 v[34:37], v[198:201], v[14:17], v[18:21]
	v_mfma_f32_16x16x32_bf16 v[18:21], v[182:185], v[190:193], v[202:205]
	v_mfma_f32_16x16x32_bf16 v[46:49], v[198:201], v[194:197], v[18:21]
	v_mfma_f32_16x16x32_bf16 v[18:21], v[222:225], v[2:5], v[248:251]
	v_mfma_f32_16x16x32_bf16 v[2:5], v[244:247], v[2:5], v[38:41]
	v_mfma_f32_16x16x32_bf16 v[18:21], v[240:243], v[14:17], v[18:21]
	v_mfma_f32_16x16x32_bf16 v[30:33], v[222:225], v[190:193], v[42:45]
	v_mfma_f32_16x16x32_bf16 v[2:5], v[230:233], v[14:17], v[2:5]
	v_mfma_f32_16x16x32_bf16 v[14:17], v[244:247], v[190:193], v[144:147]
	v_mfma_f32_16x16x32_bf16 v[30:33], v[240:243], v[194:197], v[30:33]
	v_mfma_f32_16x16x32_bf16 v[14:17], v[230:233], v[194:197], v[14:17]
	v_mfma_f32_16x16x32_bf16 v[38:41], v[174:177], v[140:143], v[162:165]
	v_mfma_f32_16x16x32_bf16 v[22:25], v[182:185], v[140:143], v[22:25]
	v_mfma_f32_16x16x32_bf16 v[54:57], v[178:181], v[206:209], v[38:41]
	v_mfma_f32_16x16x32_bf16 v[26:29], v[174:177], v[236:239], v[26:29]
	v_mfma_f32_16x16x32_bf16 v[38:41], v[198:201], v[206:209], v[22:25]
	v_mfma_f32_16x16x32_bf16 v[22:25], v[182:185], v[236:239], v[166:169]
	v_mfma_f32_16x16x32_bf16 v[10:13], v[222:225], v[236:239], v[10:13]
	v_mfma_f32_16x16x32_bf16 v[58:61], v[178:181], v[226:229], v[26:29]
	v_mfma_f32_16x16x32_bf16 v[42:45], v[198:201], v[226:229], v[22:25]
	v_mfma_f32_16x16x32_bf16 v[22:25], v[222:225], v[140:143], v[170:173]
	v_mfma_f32_16x16x32_bf16 v[26:29], v[240:243], v[226:229], v[10:13]
	v_mfma_f32_16x16x32_bf16 v[6:9], v[244:247], v[140:143], v[6:9]
	v_mfma_f32_16x16x32_bf16 v[10:13], v[244:247], v[236:239], v[186:189]
	v_mfma_f32_16x16x32_bf16 v[22:25], v[240:243], v[206:209], v[22:25]
	v_mfma_f32_16x16x32_bf16 v[6:9], v[230:233], v[206:209], v[6:9]
	v_mfma_f32_16x16x32_bf16 v[10:13], v[230:233], v[226:229], v[10:13]
	s_barrier
	s_and_saveexec_b64 s[22:23], s[6:7]
	s_cbranch_execz .LBB0_61
	s_barrier
	s_branch .LBB0_61
.LBB0_68:
	s_setprio 0
	s_mov_b64 s[4:5], 0
